# decode-row epilogues: residual/gain loads issued before combined exchange polls in both w_o and down, on top of v105
# speedup vs baseline: 1.0013x; 1.0013x over previous
.LBB0_1227:
	s_or_b64 exec, exec, s[16:17]
	v_lshl_or_b32 v236, s4, 5, v8
	v_lshl_or_b32 v238, s6, 14, v28
	v_mov_b32_e32 v239, v11
	v_ashrrev_i32_e32 v237, 31, v236
	v_lshl_add_u64 v[240:241], v[238:239], 0, v[236:237]
	v_lshl_add_u64 v[240:241], v[240:241], 1, s[8:9]
	v_readlane_b32 s50, v252, 44
	v_readlane_b32 s51, v252, 45
	s_nop 1
	v_lshl_add_u64 v[242:243], v[236:237], 2, s[50:51]
	global_load_dwordx4 v[220:223], v[240:241], off
	global_load_dwordx4 v[224:227], v[242:243], off
	global_load_dwordx4 v[228:231], v[242:243], off offset:16
	v_lshl_add_u64 v[22:23], s[14:15], 0, v[10:11]
	v_lshlrev_b32_e32 v24, 3, v8
	v_mov_b32_e32 v25, v11
	v_lshl_add_u64 v[22:23], v[22:23], 0, v[24:25]
	s_waitcnt lgkmcnt(0)
	s_waitcnt lgkmcnt(0)
	s_mov_b32 s16, 0
